# grid barriers 1-8 rewritten by hand: L1 invalidate at arrival, every workgroup polls the top generation (no per-XCC generation hop)
# speedup vs baseline: 1.0336x; 1.0018x over previous
; __device__ __forceinline__ unsigned xb_ld(unsigned* p)              { return __hip_atomic_load(p, __ATOMIC_RELAXED, __HIP_MEMORY_SCOPE_AGENT); }
; __device__ __forceinline__ unsigned xb_add(unsigned* p, unsigned v) { return __hip_atomic_fetch_add(p, v, __ATOMIC_RELAXED, __HIP_MEMORY_SCOPE_AGENT); }
; #define XB_SPIN(cond, bar) do { unsigned _sp = 0; while (cond) { __builtin_amdgcn_s_sleep(1); \
;     if ((++_sp & 255u) == 0u) { if (xb_ld(&(bar)[XB_TMO])) break; if (_sp > XB_SPIN_CAP) { atomicAdd(&(bar)[XB_TMO], 1u); break; } } } } while (0)
; __device__ __forceinline__ void xcd_barrier(const XcdBarrier& b) {
;     asm volatile("s_waitcnt vmcnt(0)" ::: "memory");
;     __syncthreads();
;     if (threadIdx.x == 0) {
;         unsigned* bar = b.bar;
;         __builtin_amdgcn_s_waitcnt(0);
;         unsigned nloc = b.st[0], nx = b.st[1];
;         if (nloc == 0u) { xcd_barrier_complete(bar, b.x, nloc, nx); b.st[0] = nloc; b.st[1] = nx; }
;         const unsigned old = xb_add(&bar[XB_XSUB(b.x)], 1u);
;         const unsigned gen = old / nloc;
;         if (old + 1u == (gen + 1u) * nloc) {
;             __builtin_amdgcn_fence(__ATOMIC_RELEASE, "agent");
;             asm volatile("s_waitcnt vmcnt(0)" ::: "memory");
;             const unsigned og = xb_add(&bar[XB_TOP], 1u);
;             const unsigned tg = og / nx;
;             if (og + 1u == (tg + 1u) * nx) xb_add(&bar[XB_TOPGEN], 1u);
;             else XB_SPIN(xb_ld(&bar[XB_TOPGEN]) == tg, bar);
;             __builtin_amdgcn_fence(__ATOMIC_ACQUIRE, "agent");
;             xb_add(&bar[XB_XGEN(b.x)], 1u);
;             asm volatile("s_waitcnt vmcnt(0)" ::: "memory");
;         } else {
;             XB_SPIN(xb_ld(&bar[XB_XGEN(b.x)]) == gen, bar);
;             __builtin_amdgcn_fence(__ATOMIC_ACQUIRE, "agent");
;             asm volatile("s_waitcnt vmcnt(0)" ::: "memory");
;         }
.LBB0_441:
	s_cmp_gt_i32 s77, 2
	s_cselect_b64 s[6:7], -1, 0
	s_and_b64 s[4:5], s[8:9], s[6:7]
	s_andn2_b64 vcc, exec, s[4:5]
	s_cbranch_vccnz .LBB0_495
	s_waitcnt vmcnt(0) lgkmcnt(0)
	s_barrier
	s_and_saveexec_b64 s[8:9], s[96:97]
	s_cbranch_execz .Lfb1_end
	buffer_inv sc1
	v_mov_b32_e32 v1, 0x20160
	ds_read2_b32 v[2:3], v1 offset1:1
	s_lshl_b32 s1, s0, 8
	s_add_u32 s10, s78, s1
	s_addc_u32 s11, s79, 0
	v_mov_b32_e32 v4, 0x1000
	v_mov_b32_e32 v5, 1
	global_atomic_add v6, v4, v5, s[10:11] offset:1024 sc0
	s_waitcnt vmcnt(0) lgkmcnt(0)
	v_readfirstlane_b32 s3, v6
	v_readfirstlane_b32 s12, v2
	v_readfirstlane_b32 s13, v3
	s_add_i32 s3, s3, 1
	s_mul_i32 s12, s12, 2
	s_cmp_lg_u32 s3, s12
	s_cbranch_scc1 .Lfb1_spin
	buffer_wbl2 sc1
	s_waitcnt vmcnt(0)
	v_mov_b32_e32 v4, 0x3000
	global_atomic_add v6, v4, v5, s[78:79] offset:1024 sc0
	s_waitcnt vmcnt(0)
	v_readfirstlane_b32 s3, v6
	s_add_i32 s3, s3, 1
	s_mul_i32 s13, s13, 2
	s_cmp_lg_u32 s3, s13
	s_cbranch_scc1 .Lfb1_spin
	v_mov_b32_e32 v4, 0x3400
	global_atomic_add v4, v5, s[78:79] offset:256
.Lfb1_spin:
	v_mov_b32_e32 v4, 0x3400
	s_mov_b32 s1, 0
.Lfb1_poll:
	global_load_dword v6, v4, s[78:79] offset:256 sc1
	s_waitcnt vmcnt(0)
	v_readfirstlane_b32 s3, v6
	s_cmp_lg_u32 s3, 1
	s_cbranch_scc1 .Lfb1_end
	s_sleep 1
	s_add_i32 s1, s1, 1
	s_cmp_lt_u32 s1, 0x8000
	s_cbranch_scc1 .Lfb1_poll
.Lfb1_end:
	s_or_b64 exec, exec, s[8:9]
	s_waitcnt vmcnt(0) lgkmcnt(0)
	s_barrier

; __device__ __forceinline__ unsigned xb_ld(unsigned* p)              { return __hip_atomic_load(p, __ATOMIC_RELAXED, __HIP_MEMORY_SCOPE_AGENT); }
; __device__ __forceinline__ unsigned xb_add(unsigned* p, unsigned v) { return __hip_atomic_fetch_add(p, v, __ATOMIC_RELAXED, __HIP_MEMORY_SCOPE_AGENT); }
; #define XB_SPIN(cond, bar) do { unsigned _sp = 0; while (cond) { __builtin_amdgcn_s_sleep(1); \
;     if ((++_sp & 255u) == 0u) { if (xb_ld(&(bar)[XB_TMO])) break; if (_sp > XB_SPIN_CAP) { atomicAdd(&(bar)[XB_TMO], 1u); break; } } } } while (0)
; __device__ __forceinline__ void xcd_barrier(const XcdBarrier& b) {
;     asm volatile("s_waitcnt vmcnt(0)" ::: "memory");
;     __syncthreads();
;     if (threadIdx.x == 0) {
;         unsigned* bar = b.bar;
;         __builtin_amdgcn_s_waitcnt(0);
;         unsigned nloc = b.st[0], nx = b.st[1];
;         if (nloc == 0u) { xcd_barrier_complete(bar, b.x, nloc, nx); b.st[0] = nloc; b.st[1] = nx; }
;         const unsigned old = xb_add(&bar[XB_XSUB(b.x)], 1u);
;         const unsigned gen = old / nloc;
;         if (old + 1u == (gen + 1u) * nloc) {
;             __builtin_amdgcn_fence(__ATOMIC_RELEASE, "agent");
;             asm volatile("s_waitcnt vmcnt(0)" ::: "memory");
;             const unsigned og = xb_add(&bar[XB_TOP], 1u);
;             const unsigned tg = og / nx;
;             if (og + 1u == (tg + 1u) * nx) xb_add(&bar[XB_TOPGEN], 1u);
;             else XB_SPIN(xb_ld(&bar[XB_TOPGEN]) == tg, bar);
;             __builtin_amdgcn_fence(__ATOMIC_ACQUIRE, "agent");
;             xb_add(&bar[XB_XGEN(b.x)], 1u);
.LBB0_694:
	s_cmp_gt_i32 s77, 3
	s_cselect_b64 s[6:7], -1, 0
	s_and_b64 s[4:5], s[44:45], s[6:7]
	s_andn2_b64 vcc, exec, s[4:5]
	s_cbranch_vccnz .LBB0_748
	s_waitcnt vmcnt(0) lgkmcnt(0)
	s_barrier
	s_and_saveexec_b64 s[8:9], s[96:97]
	s_cbranch_execz .Lfb2_end
	buffer_inv sc1
	v_mov_b32_e32 v1, 0x20160
	ds_read2_b32 v[2:3], v1 offset1:1
	s_lshl_b32 s1, s0, 8
	s_add_u32 s10, s78, s1
	s_addc_u32 s11, s79, 0
	v_mov_b32_e32 v4, 0x1000
	v_mov_b32_e32 v5, 1
	global_atomic_add v6, v4, v5, s[10:11] offset:1024 sc0
	s_waitcnt vmcnt(0) lgkmcnt(0)
	v_readfirstlane_b32 s3, v6
	v_readfirstlane_b32 s12, v2
	v_readfirstlane_b32 s13, v3
	s_add_i32 s3, s3, 1
	s_mul_i32 s12, s12, 3
	s_cmp_lg_u32 s3, s12
	s_cbranch_scc1 .Lfb2_spin
	buffer_wbl2 sc1
	s_waitcnt vmcnt(0)
	v_mov_b32_e32 v4, 0x3000
	global_atomic_add v6, v4, v5, s[78:79] offset:1024 sc0
	s_waitcnt vmcnt(0)
	v_readfirstlane_b32 s3, v6
	s_add_i32 s3, s3, 1
	s_mul_i32 s13, s13, 3
	s_cmp_lg_u32 s3, s13
	s_cbranch_scc1 .Lfb2_spin
	v_mov_b32_e32 v4, 0x3400
	global_atomic_add v4, v5, s[78:79] offset:256

; __device__ __forceinline__ unsigned xb_ld(unsigned* p)              { return __hip_atomic_load(p, __ATOMIC_RELAXED, __HIP_MEMORY_SCOPE_AGENT); }
; __device__ __forceinline__ unsigned xb_add(unsigned* p, unsigned v) { return __hip_atomic_fetch_add(p, v, __ATOMIC_RELAXED, __HIP_MEMORY_SCOPE_AGENT); }
; #define XB_SPIN(cond, bar) do { unsigned _sp = 0; while (cond) { __builtin_amdgcn_s_sleep(1); \
;     if ((++_sp & 255u) == 0u) { if (xb_ld(&(bar)[XB_TMO])) break; if (_sp > XB_SPIN_CAP) { atomicAdd(&(bar)[XB_TMO], 1u); break; } } } } while (0)
; __device__ __forceinline__ void xcd_barrier(const XcdBarrier& b) {
;     ...
;         if (old + 1u == (gen + 1u) * nloc) {
;             __builtin_amdgcn_fence(__ATOMIC_RELEASE, "agent");
;             asm volatile("s_waitcnt vmcnt(0)" ::: "memory");
;             const unsigned og = xb_add(&bar[XB_TOP], 1u);
;             const unsigned tg = og / nx;
;             if (og + 1u == (tg + 1u) * nx) xb_add(&bar[XB_TOPGEN], 1u);
;             else XB_SPIN(xb_ld(&bar[XB_TOPGEN]) == tg, bar);
;             __builtin_amdgcn_fence(__ATOMIC_ACQUIRE, "agent");
;             xb_add(&bar[XB_XGEN(b.x)], 1u);
;             asm volatile("s_waitcnt vmcnt(0)" ::: "memory");
;         } else {
;             XB_SPIN(xb_ld(&bar[XB_XGEN(b.x)]) == gen, bar);
;             __builtin_amdgcn_fence(__ATOMIC_ACQUIRE, "agent");
;             asm volatile("s_waitcnt vmcnt(0)" ::: "memory");
;         }
.Lfb2_poll:
	global_load_dword v6, v4, s[78:79] offset:256 sc1
	s_waitcnt vmcnt(0)
	v_readfirstlane_b32 s3, v6
	s_cmp_lg_u32 s3, 2
	s_cbranch_scc1 .Lfb2_end
	s_sleep 1
	s_add_i32 s1, s1, 1
	s_cmp_lt_u32 s1, 0x8000
	s_cbranch_scc1 .Lfb2_poll

; __device__ __forceinline__ unsigned xb_ld(unsigned* p)              { return __hip_atomic_load(p, __ATOMIC_RELAXED, __HIP_MEMORY_SCOPE_AGENT); }
; __device__ __forceinline__ unsigned xb_add(unsigned* p, unsigned v) { return __hip_atomic_fetch_add(p, v, __ATOMIC_RELAXED, __HIP_MEMORY_SCOPE_AGENT); }
; #define XB_SPIN(cond, bar) do { unsigned _sp = 0; while (cond) { __builtin_amdgcn_s_sleep(1); \
;     if ((++_sp & 255u) == 0u) { if (xb_ld(&(bar)[XB_TMO])) break; if (_sp > XB_SPIN_CAP) { atomicAdd(&(bar)[XB_TMO], 1u); break; } } } } while (0)
; __device__ __forceinline__ void xcd_barrier(const XcdBarrier& b) {
;     asm volatile("s_waitcnt vmcnt(0)" ::: "memory");
;     __syncthreads();
;     if (threadIdx.x == 0) {
;         unsigned* bar = b.bar;
;         __builtin_amdgcn_s_waitcnt(0);
;         unsigned nloc = b.st[0], nx = b.st[1];
;         if (nloc == 0u) { xcd_barrier_complete(bar, b.x, nloc, nx); b.st[0] = nloc; b.st[1] = nx; }
;         const unsigned old = xb_add(&bar[XB_XSUB(b.x)], 1u);
;         const unsigned gen = old / nloc;
;         if (old + 1u == (gen + 1u) * nloc) {
;             __builtin_amdgcn_fence(__ATOMIC_RELEASE, "agent");
;             asm volatile("s_waitcnt vmcnt(0)" ::: "memory");
;             const unsigned og = xb_add(&bar[XB_TOP], 1u);
;             const unsigned tg = og / nx;
;             if (og + 1u == (tg + 1u) * nx) xb_add(&bar[XB_TOPGEN], 1u);
;             else XB_SPIN(xb_ld(&bar[XB_TOPGEN]) == tg, bar);
;             __builtin_amdgcn_fence(__ATOMIC_ACQUIRE, "agent");
;             xb_add(&bar[XB_XGEN(b.x)], 1u);
.LBB0_978:
	s_cmp_gt_i32 s77, 4
	s_cselect_b64 s[6:7], -1, 0
	s_and_b64 s[4:5], s[14:15], s[6:7]
	s_andn2_b64 vcc, exec, s[4:5]
	s_cbranch_vccnz .LBB0_1032
	s_waitcnt vmcnt(0) lgkmcnt(0)
	s_barrier
	s_and_saveexec_b64 s[8:9], s[96:97]
	s_cbranch_execz .Lfb3_end
	buffer_inv sc1
	v_mov_b32_e32 v1, 0x20160
	ds_read2_b32 v[2:3], v1 offset1:1
	s_lshl_b32 s1, s0, 8
	s_add_u32 s10, s78, s1
	s_addc_u32 s11, s79, 0
	v_mov_b32_e32 v4, 0x1000
	v_mov_b32_e32 v5, 1
	global_atomic_add v6, v4, v5, s[10:11] offset:1024 sc0
	s_waitcnt vmcnt(0) lgkmcnt(0)
	v_readfirstlane_b32 s3, v6
	v_readfirstlane_b32 s12, v2
	v_readfirstlane_b32 s13, v3
	s_add_i32 s3, s3, 1
	s_mul_i32 s12, s12, 4
	s_cmp_lg_u32 s3, s12
	s_cbranch_scc1 .Lfb3_spin
	buffer_wbl2 sc1
	s_waitcnt vmcnt(0)
	v_mov_b32_e32 v4, 0x3000
	global_atomic_add v6, v4, v5, s[78:79] offset:1024 sc0
	s_waitcnt vmcnt(0)
	v_readfirstlane_b32 s3, v6
	s_add_i32 s3, s3, 1
	s_mul_i32 s13, s13, 4
	s_cmp_lg_u32 s3, s13
	s_cbranch_scc1 .Lfb3_spin
	v_mov_b32_e32 v4, 0x3400
	global_atomic_add v4, v5, s[78:79] offset:256

; __device__ __forceinline__ unsigned xb_ld(unsigned* p)              { return __hip_atomic_load(p, __ATOMIC_RELAXED, __HIP_MEMORY_SCOPE_AGENT); }
; __device__ __forceinline__ unsigned xb_add(unsigned* p, unsigned v) { return __hip_atomic_fetch_add(p, v, __ATOMIC_RELAXED, __HIP_MEMORY_SCOPE_AGENT); }
; #define XB_SPIN(cond, bar) do { unsigned _sp = 0; while (cond) { __builtin_amdgcn_s_sleep(1); \
;     if ((++_sp & 255u) == 0u) { if (xb_ld(&(bar)[XB_TMO])) break; if (_sp > XB_SPIN_CAP) { atomicAdd(&(bar)[XB_TMO], 1u); break; } } } } while (0)
; __device__ __forceinline__ void xcd_barrier(const XcdBarrier& b) {
;     ...
;         if (old + 1u == (gen + 1u) * nloc) {
;             __builtin_amdgcn_fence(__ATOMIC_RELEASE, "agent");
;             asm volatile("s_waitcnt vmcnt(0)" ::: "memory");
;             const unsigned og = xb_add(&bar[XB_TOP], 1u);
;             const unsigned tg = og / nx;
;             if (og + 1u == (tg + 1u) * nx) xb_add(&bar[XB_TOPGEN], 1u);
;             else XB_SPIN(xb_ld(&bar[XB_TOPGEN]) == tg, bar);
;             __builtin_amdgcn_fence(__ATOMIC_ACQUIRE, "agent");
;             xb_add(&bar[XB_XGEN(b.x)], 1u);
;             asm volatile("s_waitcnt vmcnt(0)" ::: "memory");
;         } else {
;             XB_SPIN(xb_ld(&bar[XB_XGEN(b.x)]) == gen, bar);
;             __builtin_amdgcn_fence(__ATOMIC_ACQUIRE, "agent");
;             asm volatile("s_waitcnt vmcnt(0)" ::: "memory");
;         }
.Lfb3_poll:
	global_load_dword v6, v4, s[78:79] offset:256 sc1
	s_waitcnt vmcnt(0)
	v_readfirstlane_b32 s3, v6
	s_cmp_lg_u32 s3, 3
	s_cbranch_scc1 .Lfb3_end
	s_sleep 1
	s_add_i32 s1, s1, 1
	s_cmp_lt_u32 s1, 0x8000
	s_cbranch_scc1 .Lfb3_poll

; __device__ __forceinline__ unsigned xb_ld(unsigned* p)              { return __hip_atomic_load(p, __ATOMIC_RELAXED, __HIP_MEMORY_SCOPE_AGENT); }
; __device__ __forceinline__ unsigned xb_add(unsigned* p, unsigned v) { return __hip_atomic_fetch_add(p, v, __ATOMIC_RELAXED, __HIP_MEMORY_SCOPE_AGENT); }
; #define XB_SPIN(cond, bar) do { unsigned _sp = 0; while (cond) { __builtin_amdgcn_s_sleep(1); \
;     if ((++_sp & 255u) == 0u) { if (xb_ld(&(bar)[XB_TMO])) break; if (_sp > XB_SPIN_CAP) { atomicAdd(&(bar)[XB_TMO], 1u); break; } } } } while (0)
; __device__ __forceinline__ void xcd_barrier(const XcdBarrier& b) {
;     asm volatile("s_waitcnt vmcnt(0)" ::: "memory");
;     __syncthreads();
;     if (threadIdx.x == 0) {
;         unsigned* bar = b.bar;
;         __builtin_amdgcn_s_waitcnt(0);
;         unsigned nloc = b.st[0], nx = b.st[1];
;         if (nloc == 0u) { xcd_barrier_complete(bar, b.x, nloc, nx); b.st[0] = nloc; b.st[1] = nx; }
;         const unsigned old = xb_add(&bar[XB_XSUB(b.x)], 1u);
;         const unsigned gen = old / nloc;
;         if (old + 1u == (gen + 1u) * nloc) {
;             __builtin_amdgcn_fence(__ATOMIC_RELEASE, "agent");
;             asm volatile("s_waitcnt vmcnt(0)" ::: "memory");
;             const unsigned og = xb_add(&bar[XB_TOP], 1u);
;             const unsigned tg = og / nx;
;             if (og + 1u == (tg + 1u) * nx) xb_add(&bar[XB_TOPGEN], 1u);
;             else XB_SPIN(xb_ld(&bar[XB_TOPGEN]) == tg, bar);
;             __builtin_amdgcn_fence(__ATOMIC_ACQUIRE, "agent");
;             xb_add(&bar[XB_XGEN(b.x)], 1u);
.LBB0_1058:
	s_cmp_gt_i32 s77, 5
	s_cselect_b64 s[6:7], -1, 0
	s_and_b64 s[4:5], s[22:23], s[6:7]
	s_andn2_b64 vcc, exec, s[4:5]
	s_cbranch_vccnz .LBB0_1112
	s_waitcnt vmcnt(0) lgkmcnt(0)
	s_barrier
	s_and_saveexec_b64 s[8:9], s[96:97]
	s_cbranch_execz .Lfb4_end
	buffer_inv sc1
	v_mov_b32_e32 v1, 0x20160
	ds_read2_b32 v[2:3], v1 offset1:1
	s_lshl_b32 s1, s0, 8
	s_add_u32 s10, s78, s1
	s_addc_u32 s11, s79, 0
	v_mov_b32_e32 v4, 0x1000
	v_mov_b32_e32 v5, 1
	global_atomic_add v6, v4, v5, s[10:11] offset:1024 sc0
	s_waitcnt vmcnt(0) lgkmcnt(0)
	v_readfirstlane_b32 s3, v6
	v_readfirstlane_b32 s12, v2
	v_readfirstlane_b32 s13, v3
	s_add_i32 s3, s3, 1
	s_mul_i32 s12, s12, 5
	s_cmp_lg_u32 s3, s12
	s_cbranch_scc1 .Lfb4_spin
	buffer_wbl2 sc1
	s_waitcnt vmcnt(0)
	v_mov_b32_e32 v4, 0x3000
	global_atomic_add v6, v4, v5, s[78:79] offset:1024 sc0
	s_waitcnt vmcnt(0)
	v_readfirstlane_b32 s3, v6
	s_add_i32 s3, s3, 1
	s_mul_i32 s13, s13, 5
	s_cmp_lg_u32 s3, s13
	s_cbranch_scc1 .Lfb4_spin
	v_mov_b32_e32 v4, 0x3400
	global_atomic_add v4, v5, s[78:79] offset:256

; __device__ __forceinline__ unsigned xb_ld(unsigned* p)              { return __hip_atomic_load(p, __ATOMIC_RELAXED, __HIP_MEMORY_SCOPE_AGENT); }
; __device__ __forceinline__ unsigned xb_add(unsigned* p, unsigned v) { return __hip_atomic_fetch_add(p, v, __ATOMIC_RELAXED, __HIP_MEMORY_SCOPE_AGENT); }
; #define XB_SPIN(cond, bar) do { unsigned _sp = 0; while (cond) { __builtin_amdgcn_s_sleep(1); \
;     if ((++_sp & 255u) == 0u) { if (xb_ld(&(bar)[XB_TMO])) break; if (_sp > XB_SPIN_CAP) { atomicAdd(&(bar)[XB_TMO], 1u); break; } } } } while (0)
; __device__ __forceinline__ void xcd_barrier(const XcdBarrier& b) {
;     ...
;         if (old + 1u == (gen + 1u) * nloc) {
;             __builtin_amdgcn_fence(__ATOMIC_RELEASE, "agent");
;             asm volatile("s_waitcnt vmcnt(0)" ::: "memory");
;             const unsigned og = xb_add(&bar[XB_TOP], 1u);
;             const unsigned tg = og / nx;
;             if (og + 1u == (tg + 1u) * nx) xb_add(&bar[XB_TOPGEN], 1u);
;             else XB_SPIN(xb_ld(&bar[XB_TOPGEN]) == tg, bar);
;             __builtin_amdgcn_fence(__ATOMIC_ACQUIRE, "agent");
;             xb_add(&bar[XB_XGEN(b.x)], 1u);
;             asm volatile("s_waitcnt vmcnt(0)" ::: "memory");
;         } else {
;             XB_SPIN(xb_ld(&bar[XB_XGEN(b.x)]) == gen, bar);
;             __builtin_amdgcn_fence(__ATOMIC_ACQUIRE, "agent");
;             asm volatile("s_waitcnt vmcnt(0)" ::: "memory");
;         }
.Lfb4_poll:
	global_load_dword v6, v4, s[78:79] offset:256 sc1
	s_waitcnt vmcnt(0)
	v_readfirstlane_b32 s3, v6
	s_cmp_lg_u32 s3, 4
	s_cbranch_scc1 .Lfb4_end
	s_sleep 1
	s_add_i32 s1, s1, 1
	s_cmp_lt_u32 s1, 0x8000
	s_cbranch_scc1 .Lfb4_poll

; __device__ __forceinline__ unsigned xb_ld(unsigned* p)              { return __hip_atomic_load(p, __ATOMIC_RELAXED, __HIP_MEMORY_SCOPE_AGENT); }
; __device__ __forceinline__ unsigned xb_add(unsigned* p, unsigned v) { return __hip_atomic_fetch_add(p, v, __ATOMIC_RELAXED, __HIP_MEMORY_SCOPE_AGENT); }
; #define XB_SPIN(cond, bar) do { unsigned _sp = 0; while (cond) { __builtin_amdgcn_s_sleep(1); \
;     if ((++_sp & 255u) == 0u) { if (xb_ld(&(bar)[XB_TMO])) break; if (_sp > XB_SPIN_CAP) { atomicAdd(&(bar)[XB_TMO], 1u); break; } } } } while (0)
; __device__ __forceinline__ void xcd_barrier(const XcdBarrier& b) {
;     asm volatile("s_waitcnt vmcnt(0)" ::: "memory");
;     __syncthreads();
;     if (threadIdx.x == 0) {
;         unsigned* bar = b.bar;
;         __builtin_amdgcn_s_waitcnt(0);
;         unsigned nloc = b.st[0], nx = b.st[1];
;         if (nloc == 0u) { xcd_barrier_complete(bar, b.x, nloc, nx); b.st[0] = nloc; b.st[1] = nx; }
;         const unsigned old = xb_add(&bar[XB_XSUB(b.x)], 1u);
;         const unsigned gen = old / nloc;
;         if (old + 1u == (gen + 1u) * nloc) {
;             __builtin_amdgcn_fence(__ATOMIC_RELEASE, "agent");
;             asm volatile("s_waitcnt vmcnt(0)" ::: "memory");
;             const unsigned og = xb_add(&bar[XB_TOP], 1u);
;             const unsigned tg = og / nx;
;             if (og + 1u == (tg + 1u) * nx) xb_add(&bar[XB_TOPGEN], 1u);
;             else XB_SPIN(xb_ld(&bar[XB_TOPGEN]) == tg, bar);
;             __builtin_amdgcn_fence(__ATOMIC_ACQUIRE, "agent");
;             xb_add(&bar[XB_XGEN(b.x)], 1u);
.LBB0_1157:
	s_cmp_gt_i32 s77, 6
	s_waitcnt lgkmcnt(0)
	s_cselect_b64 s[6:7], -1, 0
	s_and_b64 s[4:5], s[20:21], s[6:7]
	s_andn2_b64 vcc, exec, s[4:5]
	s_cbranch_vccnz .LBB0_1211
	s_waitcnt vmcnt(0) lgkmcnt(0)
	s_barrier
	s_and_saveexec_b64 s[8:9], s[96:97]
	s_cbranch_execz .Lfb5_end
	buffer_inv sc1
	v_mov_b32_e32 v1, 0x20160
	ds_read2_b32 v[2:3], v1 offset1:1
	s_lshl_b32 s1, s0, 8
	s_add_u32 s10, s78, s1
	s_addc_u32 s11, s79, 0
	v_mov_b32_e32 v4, 0x1000
	v_mov_b32_e32 v5, 1
	global_atomic_add v6, v4, v5, s[10:11] offset:1024 sc0
	s_waitcnt vmcnt(0) lgkmcnt(0)
	v_readfirstlane_b32 s3, v6
	v_readfirstlane_b32 s12, v2
	v_readfirstlane_b32 s13, v3
	s_add_i32 s3, s3, 1
	s_mul_i32 s12, s12, 6
	s_cmp_lg_u32 s3, s12
	s_cbranch_scc1 .Lfb5_spin
	buffer_wbl2 sc1
	s_waitcnt vmcnt(0)
	v_mov_b32_e32 v4, 0x3000
	global_atomic_add v6, v4, v5, s[78:79] offset:1024 sc0
	s_waitcnt vmcnt(0)
	v_readfirstlane_b32 s3, v6
	s_add_i32 s3, s3, 1
	s_mul_i32 s13, s13, 6
	s_cmp_lg_u32 s3, s13
	s_cbranch_scc1 .Lfb5_spin
	v_mov_b32_e32 v4, 0x3400
	global_atomic_add v4, v5, s[78:79] offset:256

; __device__ __forceinline__ unsigned xb_ld(unsigned* p)              { return __hip_atomic_load(p, __ATOMIC_RELAXED, __HIP_MEMORY_SCOPE_AGENT); }
; __device__ __forceinline__ unsigned xb_add(unsigned* p, unsigned v) { return __hip_atomic_fetch_add(p, v, __ATOMIC_RELAXED, __HIP_MEMORY_SCOPE_AGENT); }
; #define XB_SPIN(cond, bar) do { unsigned _sp = 0; while (cond) { __builtin_amdgcn_s_sleep(1); \
;     if ((++_sp & 255u) == 0u) { if (xb_ld(&(bar)[XB_TMO])) break; if (_sp > XB_SPIN_CAP) { atomicAdd(&(bar)[XB_TMO], 1u); break; } } } } while (0)
; __device__ __forceinline__ void xcd_barrier(const XcdBarrier& b) {
;     ...
;         if (old + 1u == (gen + 1u) * nloc) {
;             __builtin_amdgcn_fence(__ATOMIC_RELEASE, "agent");
;             asm volatile("s_waitcnt vmcnt(0)" ::: "memory");
;             const unsigned og = xb_add(&bar[XB_TOP], 1u);
;             const unsigned tg = og / nx;
;             if (og + 1u == (tg + 1u) * nx) xb_add(&bar[XB_TOPGEN], 1u);
;             else XB_SPIN(xb_ld(&bar[XB_TOPGEN]) == tg, bar);
;             __builtin_amdgcn_fence(__ATOMIC_ACQUIRE, "agent");
;             xb_add(&bar[XB_XGEN(b.x)], 1u);
;             asm volatile("s_waitcnt vmcnt(0)" ::: "memory");
;         } else {
;             XB_SPIN(xb_ld(&bar[XB_XGEN(b.x)]) == gen, bar);
;             __builtin_amdgcn_fence(__ATOMIC_ACQUIRE, "agent");
;             asm volatile("s_waitcnt vmcnt(0)" ::: "memory");
;         }
.Lfb5_poll:
	global_load_dword v6, v4, s[78:79] offset:256 sc1
	s_waitcnt vmcnt(0)
	v_readfirstlane_b32 s3, v6
	s_cmp_lg_u32 s3, 5
	s_cbranch_scc1 .Lfb5_end
	s_sleep 1
	s_add_i32 s1, s1, 1
	s_cmp_lt_u32 s1, 0x8000
	s_cbranch_scc1 .Lfb5_poll

; __device__ __forceinline__ unsigned xb_ld(unsigned* p)              { return __hip_atomic_load(p, __ATOMIC_RELAXED, __HIP_MEMORY_SCOPE_AGENT); }
; __device__ __forceinline__ unsigned xb_add(unsigned* p, unsigned v) { return __hip_atomic_fetch_add(p, v, __ATOMIC_RELAXED, __HIP_MEMORY_SCOPE_AGENT); }
; #define XB_SPIN(cond, bar) do { unsigned _sp = 0; while (cond) { __builtin_amdgcn_s_sleep(1); \
;     if ((++_sp & 255u) == 0u) { if (xb_ld(&(bar)[XB_TMO])) break; if (_sp > XB_SPIN_CAP) { atomicAdd(&(bar)[XB_TMO], 1u); break; } } } } while (0)
; __device__ __forceinline__ void xcd_barrier(const XcdBarrier& b) {
;     asm volatile("s_waitcnt vmcnt(0)" ::: "memory");
;     __syncthreads();
;     if (threadIdx.x == 0) {
;         unsigned* bar = b.bar;
;         __builtin_amdgcn_s_waitcnt(0);
;         unsigned nloc = b.st[0], nx = b.st[1];
;         if (nloc == 0u) { xcd_barrier_complete(bar, b.x, nloc, nx); b.st[0] = nloc; b.st[1] = nx; }
;         const unsigned old = xb_add(&bar[XB_XSUB(b.x)], 1u);
;         const unsigned gen = old / nloc;
;         if (old + 1u == (gen + 1u) * nloc) {
;             __builtin_amdgcn_fence(__ATOMIC_RELEASE, "agent");
;             asm volatile("s_waitcnt vmcnt(0)" ::: "memory");
;             const unsigned og = xb_add(&bar[XB_TOP], 1u);
;             const unsigned tg = og / nx;
;             if (og + 1u == (tg + 1u) * nx) xb_add(&bar[XB_TOPGEN], 1u);
;             else XB_SPIN(xb_ld(&bar[XB_TOPGEN]) == tg, bar);
;             __builtin_amdgcn_fence(__ATOMIC_ACQUIRE, "agent");
;             xb_add(&bar[XB_XGEN(b.x)], 1u);
.LBB0_1300:
	s_cmp_gt_i32 s77, 7
	s_cselect_b64 s[6:7], -1, 0
	s_and_b64 s[4:5], s[30:31], s[6:7]
	s_andn2_b64 vcc, exec, s[4:5]
	s_cbranch_vccnz .LBB0_1354
	s_waitcnt vmcnt(0) lgkmcnt(0)
	s_barrier
	s_and_saveexec_b64 s[8:9], s[96:97]
	s_cbranch_execz .Lfb6_end
	buffer_inv sc1
	v_mov_b32_e32 v1, 0x20160
	ds_read2_b32 v[2:3], v1 offset1:1
	s_lshl_b32 s1, s0, 8
	s_add_u32 s10, s78, s1
	s_addc_u32 s11, s79, 0
	v_mov_b32_e32 v4, 0x1000
	v_mov_b32_e32 v5, 1
	global_atomic_add v6, v4, v5, s[10:11] offset:1024 sc0
	s_waitcnt vmcnt(0) lgkmcnt(0)
	v_readfirstlane_b32 s3, v6
	v_readfirstlane_b32 s12, v2
	v_readfirstlane_b32 s13, v3
	s_add_i32 s3, s3, 1
	s_mul_i32 s12, s12, 7
	s_cmp_lg_u32 s3, s12
	s_cbranch_scc1 .Lfb6_spin
	buffer_wbl2 sc1
	s_waitcnt vmcnt(0)
	v_mov_b32_e32 v4, 0x3000
	global_atomic_add v6, v4, v5, s[78:79] offset:1024 sc0
	s_waitcnt vmcnt(0)
	v_readfirstlane_b32 s3, v6
	s_add_i32 s3, s3, 1
	s_mul_i32 s13, s13, 7
	s_cmp_lg_u32 s3, s13
	s_cbranch_scc1 .Lfb6_spin
	v_mov_b32_e32 v4, 0x3400
	global_atomic_add v4, v5, s[78:79] offset:256

; __device__ __forceinline__ unsigned xb_ld(unsigned* p)              { return __hip_atomic_load(p, __ATOMIC_RELAXED, __HIP_MEMORY_SCOPE_AGENT); }
; __device__ __forceinline__ unsigned xb_add(unsigned* p, unsigned v) { return __hip_atomic_fetch_add(p, v, __ATOMIC_RELAXED, __HIP_MEMORY_SCOPE_AGENT); }
; #define XB_SPIN(cond, bar) do { unsigned _sp = 0; while (cond) { __builtin_amdgcn_s_sleep(1); \
;     if ((++_sp & 255u) == 0u) { if (xb_ld(&(bar)[XB_TMO])) break; if (_sp > XB_SPIN_CAP) { atomicAdd(&(bar)[XB_TMO], 1u); break; } } } } while (0)
; __device__ __forceinline__ void xcd_barrier(const XcdBarrier& b) {
;     ...
;         if (old + 1u == (gen + 1u) * nloc) {
;             __builtin_amdgcn_fence(__ATOMIC_RELEASE, "agent");
;             asm volatile("s_waitcnt vmcnt(0)" ::: "memory");
;             const unsigned og = xb_add(&bar[XB_TOP], 1u);
;             const unsigned tg = og / nx;
;             if (og + 1u == (tg + 1u) * nx) xb_add(&bar[XB_TOPGEN], 1u);
;             else XB_SPIN(xb_ld(&bar[XB_TOPGEN]) == tg, bar);
;             __builtin_amdgcn_fence(__ATOMIC_ACQUIRE, "agent");
;             xb_add(&bar[XB_XGEN(b.x)], 1u);
;             asm volatile("s_waitcnt vmcnt(0)" ::: "memory");
;         } else {
;             XB_SPIN(xb_ld(&bar[XB_XGEN(b.x)]) == gen, bar);
;             __builtin_amdgcn_fence(__ATOMIC_ACQUIRE, "agent");
;             asm volatile("s_waitcnt vmcnt(0)" ::: "memory");
;         }
.Lfb6_poll:
	global_load_dword v6, v4, s[78:79] offset:256 sc1
	s_waitcnt vmcnt(0)
	v_readfirstlane_b32 s3, v6
	s_cmp_lg_u32 s3, 6
	s_cbranch_scc1 .Lfb6_end
	s_sleep 1
	s_add_i32 s1, s1, 1
	s_cmp_lt_u32 s1, 0x8000
	s_cbranch_scc1 .Lfb6_poll

; __device__ __forceinline__ unsigned xb_ld(unsigned* p)              { return __hip_atomic_load(p, __ATOMIC_RELAXED, __HIP_MEMORY_SCOPE_AGENT); }
; __device__ __forceinline__ unsigned xb_add(unsigned* p, unsigned v) { return __hip_atomic_fetch_add(p, v, __ATOMIC_RELAXED, __HIP_MEMORY_SCOPE_AGENT); }
; #define XB_SPIN(cond, bar) do { unsigned _sp = 0; while (cond) { __builtin_amdgcn_s_sleep(1); \
;     if ((++_sp & 255u) == 0u) { if (xb_ld(&(bar)[XB_TMO])) break; if (_sp > XB_SPIN_CAP) { atomicAdd(&(bar)[XB_TMO], 1u); break; } } } } while (0)
; __device__ __forceinline__ void xcd_barrier(const XcdBarrier& b) {
;     asm volatile("s_waitcnt vmcnt(0)" ::: "memory");
;     __syncthreads();
;     if (threadIdx.x == 0) {
;         unsigned* bar = b.bar;
;         __builtin_amdgcn_s_waitcnt(0);
;         unsigned nloc = b.st[0], nx = b.st[1];
;         if (nloc == 0u) { xcd_barrier_complete(bar, b.x, nloc, nx); b.st[0] = nloc; b.st[1] = nx; }
;         const unsigned old = xb_add(&bar[XB_XSUB(b.x)], 1u);
;         const unsigned gen = old / nloc;
;         if (old + 1u == (gen + 1u) * nloc) {
;             __builtin_amdgcn_fence(__ATOMIC_RELEASE, "agent");
;             asm volatile("s_waitcnt vmcnt(0)" ::: "memory");
;             const unsigned og = xb_add(&bar[XB_TOP], 1u);
;             const unsigned tg = og / nx;
;             if (og + 1u == (tg + 1u) * nx) xb_add(&bar[XB_TOPGEN], 1u);
;             else XB_SPIN(xb_ld(&bar[XB_TOPGEN]) == tg, bar);
;             __builtin_amdgcn_fence(__ATOMIC_ACQUIRE, "agent");
;             xb_add(&bar[XB_XGEN(b.x)], 1u);
.LBB0_1383:
	s_cmp_gt_i32 s77, 8
	s_cselect_b64 s[6:7], -1, 0
	s_and_b64 s[4:5], s[10:11], s[6:7]
	s_andn2_b64 vcc, exec, s[4:5]
	s_cbranch_vccnz .LBB0_1437
	s_waitcnt vmcnt(0) lgkmcnt(0)
	s_barrier
	s_and_saveexec_b64 s[8:9], s[96:97]
	s_cbranch_execz .Lfb7_end
	buffer_inv sc1
	v_mov_b32_e32 v1, 0x20160
	ds_read2_b32 v[2:3], v1 offset1:1
	s_lshl_b32 s1, s0, 8
	s_add_u32 s10, s78, s1
	s_addc_u32 s11, s79, 0
	v_mov_b32_e32 v4, 0x1000
	v_mov_b32_e32 v5, 1
	global_atomic_add v6, v4, v5, s[10:11] offset:1024 sc0
	s_waitcnt vmcnt(0) lgkmcnt(0)
	v_readfirstlane_b32 s3, v6
	v_readfirstlane_b32 s12, v2
	v_readfirstlane_b32 s13, v3
	s_add_i32 s3, s3, 1
	s_mul_i32 s12, s12, 8
	s_cmp_lg_u32 s3, s12
	s_cbranch_scc1 .Lfb7_spin
	buffer_wbl2 sc1
	s_waitcnt vmcnt(0)
	v_mov_b32_e32 v4, 0x3000
	global_atomic_add v6, v4, v5, s[78:79] offset:1024 sc0
	s_waitcnt vmcnt(0)
	v_readfirstlane_b32 s3, v6
	s_add_i32 s3, s3, 1
	s_mul_i32 s13, s13, 8
	s_cmp_lg_u32 s3, s13
	s_cbranch_scc1 .Lfb7_spin
	v_mov_b32_e32 v4, 0x3400
	global_atomic_add v4, v5, s[78:79] offset:256

; __device__ __forceinline__ unsigned xb_ld(unsigned* p)              { return __hip_atomic_load(p, __ATOMIC_RELAXED, __HIP_MEMORY_SCOPE_AGENT); }
; __device__ __forceinline__ unsigned xb_add(unsigned* p, unsigned v) { return __hip_atomic_fetch_add(p, v, __ATOMIC_RELAXED, __HIP_MEMORY_SCOPE_AGENT); }
; #define XB_SPIN(cond, bar) do { unsigned _sp = 0; while (cond) { __builtin_amdgcn_s_sleep(1); \
;     if ((++_sp & 255u) == 0u) { if (xb_ld(&(bar)[XB_TMO])) break; if (_sp > XB_SPIN_CAP) { atomicAdd(&(bar)[XB_TMO], 1u); break; } } } } while (0)
; __device__ __forceinline__ void xcd_barrier(const XcdBarrier& b) {
;     ...
;         if (old + 1u == (gen + 1u) * nloc) {
;             __builtin_amdgcn_fence(__ATOMIC_RELEASE, "agent");
;             asm volatile("s_waitcnt vmcnt(0)" ::: "memory");
;             const unsigned og = xb_add(&bar[XB_TOP], 1u);
;             const unsigned tg = og / nx;
;             if (og + 1u == (tg + 1u) * nx) xb_add(&bar[XB_TOPGEN], 1u);
;             else XB_SPIN(xb_ld(&bar[XB_TOPGEN]) == tg, bar);
;             __builtin_amdgcn_fence(__ATOMIC_ACQUIRE, "agent");
;             xb_add(&bar[XB_XGEN(b.x)], 1u);
;             asm volatile("s_waitcnt vmcnt(0)" ::: "memory");
;         } else {
;             XB_SPIN(xb_ld(&bar[XB_XGEN(b.x)]) == gen, bar);
;             __builtin_amdgcn_fence(__ATOMIC_ACQUIRE, "agent");
;             asm volatile("s_waitcnt vmcnt(0)" ::: "memory");
;         }
.Lfb7_poll:
	global_load_dword v6, v4, s[78:79] offset:256 sc1
	s_waitcnt vmcnt(0)
	v_readfirstlane_b32 s3, v6
	s_cmp_lg_u32 s3, 7
	s_cbranch_scc1 .Lfb7_end
	s_sleep 1
	s_add_i32 s1, s1, 1
	s_cmp_lt_u32 s1, 0x8000
	s_cbranch_scc1 .Lfb7_poll

; __device__ __forceinline__ unsigned xb_ld(unsigned* p)              { return __hip_atomic_load(p, __ATOMIC_RELAXED, __HIP_MEMORY_SCOPE_AGENT); }
; __device__ __forceinline__ unsigned xb_add(unsigned* p, unsigned v) { return __hip_atomic_fetch_add(p, v, __ATOMIC_RELAXED, __HIP_MEMORY_SCOPE_AGENT); }
; #define XB_SPIN(cond, bar) do { unsigned _sp = 0; while (cond) { __builtin_amdgcn_s_sleep(1); \
;     if ((++_sp & 255u) == 0u) { if (xb_ld(&(bar)[XB_TMO])) break; if (_sp > XB_SPIN_CAP) { atomicAdd(&(bar)[XB_TMO], 1u); break; } } } } while (0)
; __device__ __forceinline__ void xcd_barrier(const XcdBarrier& b) {
;     asm volatile("s_waitcnt vmcnt(0)" ::: "memory");
;     __syncthreads();
;     if (threadIdx.x == 0) {
;         unsigned* bar = b.bar;
;         __builtin_amdgcn_s_waitcnt(0);
;         unsigned nloc = b.st[0], nx = b.st[1];
;         if (nloc == 0u) { xcd_barrier_complete(bar, b.x, nloc, nx); b.st[0] = nloc; b.st[1] = nx; }
;         const unsigned old = xb_add(&bar[XB_XSUB(b.x)], 1u);
;         const unsigned gen = old / nloc;
;         if (old + 1u == (gen + 1u) * nloc) {
;             __builtin_amdgcn_fence(__ATOMIC_RELEASE, "agent");
;             asm volatile("s_waitcnt vmcnt(0)" ::: "memory");
;             const unsigned og = xb_add(&bar[XB_TOP], 1u);
;             const unsigned tg = og / nx;
;             if (og + 1u == (tg + 1u) * nx) xb_add(&bar[XB_TOPGEN], 1u);
;             else XB_SPIN(xb_ld(&bar[XB_TOPGEN]) == tg, bar);
;             __builtin_amdgcn_fence(__ATOMIC_ACQUIRE, "agent");
;             xb_add(&bar[XB_XGEN(b.x)], 1u);
.LBB0_1480:
	s_cmp_gt_i32 s77, 9
	s_cselect_b64 s[6:7], -1, 0
	s_and_b64 s[4:5], s[16:17], s[6:7]
	s_andn2_b64 vcc, exec, s[4:5]
	s_cbranch_vccnz .LBB0_1534
	s_waitcnt vmcnt(0) lgkmcnt(0)
	s_barrier
	s_and_saveexec_b64 s[8:9], s[96:97]
	s_cbranch_execz .Lfb8_end
	buffer_inv sc1
	v_mov_b32_e32 v1, 0x20160
	ds_read2_b32 v[2:3], v1 offset1:1
	s_lshl_b32 s1, s0, 8
	s_add_u32 s10, s78, s1
	s_addc_u32 s11, s79, 0
	v_mov_b32_e32 v4, 0x1000
	v_mov_b32_e32 v5, 1
	global_atomic_add v6, v4, v5, s[10:11] offset:1024 sc0
	s_waitcnt vmcnt(0) lgkmcnt(0)
	v_readfirstlane_b32 s3, v6
	v_readfirstlane_b32 s12, v2
	v_readfirstlane_b32 s13, v3
	s_add_i32 s3, s3, 1
	s_mul_i32 s12, s12, 9
	s_cmp_lg_u32 s3, s12
	s_cbranch_scc1 .Lfb8_spin
	buffer_wbl2 sc1
	s_waitcnt vmcnt(0)
	v_mov_b32_e32 v4, 0x3000
	global_atomic_add v6, v4, v5, s[78:79] offset:1024 sc0
	s_waitcnt vmcnt(0)
	v_readfirstlane_b32 s3, v6
	s_add_i32 s3, s3, 1
	s_mul_i32 s13, s13, 9
	s_cmp_lg_u32 s3, s13
	s_cbranch_scc1 .Lfb8_spin
	v_mov_b32_e32 v4, 0x3400
	global_atomic_add v4, v5, s[78:79] offset:256

; __device__ __forceinline__ unsigned xb_ld(unsigned* p)              { return __hip_atomic_load(p, __ATOMIC_RELAXED, __HIP_MEMORY_SCOPE_AGENT); }
; __device__ __forceinline__ unsigned xb_add(unsigned* p, unsigned v) { return __hip_atomic_fetch_add(p, v, __ATOMIC_RELAXED, __HIP_MEMORY_SCOPE_AGENT); }
; #define XB_SPIN(cond, bar) do { unsigned _sp = 0; while (cond) { __builtin_amdgcn_s_sleep(1); \
;     if ((++_sp & 255u) == 0u) { if (xb_ld(&(bar)[XB_TMO])) break; if (_sp > XB_SPIN_CAP) { atomicAdd(&(bar)[XB_TMO], 1u); break; } } } } while (0)
; __device__ __forceinline__ void xcd_barrier(const XcdBarrier& b) {
;     ...
;         if (old + 1u == (gen + 1u) * nloc) {
;             __builtin_amdgcn_fence(__ATOMIC_RELEASE, "agent");
;             asm volatile("s_waitcnt vmcnt(0)" ::: "memory");
;             const unsigned og = xb_add(&bar[XB_TOP], 1u);
;             const unsigned tg = og / nx;
;             if (og + 1u == (tg + 1u) * nx) xb_add(&bar[XB_TOPGEN], 1u);
;             else XB_SPIN(xb_ld(&bar[XB_TOPGEN]) == tg, bar);
;             __builtin_amdgcn_fence(__ATOMIC_ACQUIRE, "agent");
;             xb_add(&bar[XB_XGEN(b.x)], 1u);
;             asm volatile("s_waitcnt vmcnt(0)" ::: "memory");
;         } else {
;             XB_SPIN(xb_ld(&bar[XB_XGEN(b.x)]) == gen, bar);
;             __builtin_amdgcn_fence(__ATOMIC_ACQUIRE, "agent");
;             asm volatile("s_waitcnt vmcnt(0)" ::: "memory");
;         }
.Lfb8_poll:
	global_load_dword v6, v4, s[78:79] offset:256 sc1
	s_waitcnt vmcnt(0)
	v_readfirstlane_b32 s3, v6
	s_cmp_lg_u32 s3, 8
	s_cbranch_scc1 .Lfb8_end
	s_sleep 1
	s_add_i32 s1, s1, 1
	s_cmp_lt_u32 s1, 0x8000
	s_cbranch_scc1 .Lfb8_poll
